# group barriers around the up GEMM; groups verified (census of XCC ids) to share one L2 skip the L2 write-back
# speedup vs baseline: 1.0157x; 1.0157x over previous
; #define LAS __attribute__((address_space(3)))
; __device__ __forceinline__ unsigned xb_add(unsigned* p, unsigned v) { return __hip_atomic_fetch_add(p, v, __ATOMIC_RELAXED, __HIP_MEMORY_SCOPE_AGENT); }
; __device__ __forceinline__ unsigned xb_xcc_id() { return (unsigned)__builtin_amdgcn_s_getreg((3 << 11) | 20) & 0xFu; }
; __device__ __forceinline__ XcdBarrier xcd_barrier_post(unsigned* bar, volatile LAS unsigned* st) {
;     XcdBarrier b; b.bar = bar; b.x = xb_xcc_id(); b.st = st;
;     if (threadIdx.x == 0) (void)xb_add(&bar[XB_XCNT(b.x)], 1u);
;     return b;
; }
; __device__ __forceinline__ void xcd_barrier(const XcdBarrier& b) {
;     asm volatile("s_waitcnt vmcnt(0)" ::: "memory");
;     __syncthreads();
;     if (threadIdx.x == 0) {
;         unsigned* bar = b.bar;
;         __builtin_amdgcn_s_waitcnt(0);
;         unsigned nloc = b.st[0], nx = b.st[1];
;         if (nloc == 0u) { xcd_barrier_complete(bar, b.x, nloc, nx); b.st[0] = nloc; b.st[1] = nx; }
;         const unsigned old = xb_add(&bar[XB_XSUB(b.x)], 1u);
.LBB0_729:
	s_waitcnt vmcnt(0)
	s_waitcnt vmcnt(0) lgkmcnt(0)
	s_barrier
	s_mov_b64 s[0:1], exec
	v_readlane_b32 s2, v247, 37
	v_readlane_b32 s3, v247, 38
	s_and_b64 s[2:3], s[0:1], s[2:3]
	s_mov_b64 exec, s[2:3]
	s_cbranch_execz .LBB0_781
	v_readlane_b32 s2, v247, 36
	s_nop 0
	s_and_b32 s2, s2, 7
	s_lshl_b32 s2, s2, 2
	s_lshl_b32 s3, 1, s2
	v_mov_b32_e32 v2, s3
	s_and_b32 s2, s90, 31
	s_lshl_b32 s2, s2, 6
	s_add_u32 s2, s62, s2
	s_addc_u32 s3, s63, 0
	s_add_u32 s2, s2, 0xa000
	s_addc_u32 s3, s3, 0
	v_mov_b32_e32 v1, 0
	global_atomic_add v1, v2, s[2:3]
	s_add_i32 s2, 0, 0x24160
	v_mov_b32_e32 v1, s2
	s_waitcnt vmcnt(0) expcnt(0) lgkmcnt(0)
	ds_read_b32 v3, v1
	s_add_i32 s2, 0, 0x24164
	v_mov_b32_e32 v1, s2
	ds_read_b32 v1, v1
	s_waitcnt lgkmcnt(1)
	v_cmp_ne_u32_e32 vcc, 0, v3
	s_cbranch_vccnz .LBB0_745
	v_readlane_b32 s2, v247, 0
	v_readlane_b32 s3, v247, 1
	s_load_dwordx2 s[6:7], s[2:3], 0x4
	s_add_u32 s2, s62, 0x4200
	s_addc_u32 s3, s63, 0
	s_add_u32 s4, s62, 0x4400
	s_addc_u32 s5, s63, 0
	s_waitcnt lgkmcnt(0)
	s_mul_i32 s33, s6, s80
	s_add_u32 s6, s62, 0x4500
	s_mul_i32 s33, s33, s7
	s_addc_u32 s7, s63, 0
	s_add_u32 s8, s62, 0x4600
	s_addc_u32 s9, s63, 0
	s_add_u32 s10, s62, 0x4700
	s_addc_u32 s11, s63, 0
	s_add_u32 s12, s62, 0x4800
	s_addc_u32 s13, s63, 0
	s_add_u32 s14, s62, 0x4900
	s_addc_u32 s15, s63, 0
	s_add_u32 s16, s62, 0x4a00
	s_addc_u32 s17, s63, 0
	s_add_u32 s18, s62, 0x4b00
	s_addc_u32 s19, s63, 0
	s_add_u32 s20, s62, 0x4c00
	s_addc_u32 s21, s63, 0
	s_add_u32 s22, s62, 0x4d00
	s_addc_u32 s23, s63, 0
	s_add_u32 s24, s62, 0x4e00
	s_addc_u32 s25, s63, 0
	s_add_u32 s26, s62, 0x4f00
	s_addc_u32 s27, s63, 0
	s_add_u32 s28, s62, 0x5000
	s_addc_u32 s29, s63, 0
	s_add_u32 s30, s62, 0x5100
	s_addc_u32 s31, s63, 0
	s_add_u32 s34, s62, 0x5200
	s_addc_u32 s35, s63, 0
	s_add_u32 s36, s62, 0x5300
	s_addc_u32 s37, s63, 0
	s_mov_b32 s44, 1
	v_mov_b32_e32 v17, 0
	s_branch .LBB0_733

; __device__ __forceinline__ unsigned xb_ld(unsigned* p)              { return __hip_atomic_load(p, __ATOMIC_RELAXED, __HIP_MEMORY_SCOPE_AGENT); }
; __device__ __forceinline__ unsigned xb_add(unsigned* p, unsigned v) { return __hip_atomic_fetch_add(p, v, __ATOMIC_RELAXED, __HIP_MEMORY_SCOPE_AGENT); }
; #define XB_SPIN(cond, bar) do { unsigned _sp = 0; while (cond) { __builtin_amdgcn_s_sleep(1); \
;     if ((++_sp & 255u) == 0u) { if (xb_ld(&(bar)[XB_TMO])) break; if (_sp > XB_SPIN_CAP) { atomicAdd(&(bar)[XB_TMO], 1u); break; } } } } while (0)
; __device__ __forceinline__ void xcd_barrier(const XcdBarrier& b) {
;     asm volatile("s_waitcnt vmcnt(0)" ::: "memory");
;     __syncthreads();
;     if (threadIdx.x == 0) {
;         unsigned* bar = b.bar;
;         __builtin_amdgcn_s_waitcnt(0);
;         unsigned nloc = b.st[0], nx = b.st[1];
;         if (nloc == 0u) { xcd_barrier_complete(bar, b.x, nloc, nx); b.st[0] = nloc; b.st[1] = nx; }
;         const unsigned old = xb_add(&bar[XB_XSUB(b.x)], 1u);
;         const unsigned gen = old / nloc;
;         if (old + 1u == (gen + 1u) * nloc) {
;             __builtin_amdgcn_fence(__ATOMIC_RELEASE, "agent");
;             asm volatile("s_waitcnt vmcnt(0)" ::: "memory");
;             const unsigned og = xb_add(&bar[XB_TOP], 1u);
;             const unsigned tg = og / nx;
;             if (og + 1u == (tg + 1u) * nx) xb_add(&bar[XB_TOPGEN], 1u);
;             else XB_SPIN(xb_ld(&bar[XB_TOPGEN]) == tg, bar);
;             __builtin_amdgcn_fence(__ATOMIC_ACQUIRE, "agent");
;             xb_add(&bar[XB_XGEN(b.x)], 1u);
;             asm volatile("s_waitcnt vmcnt(0)" ::: "memory");
;         } else {
;             XB_SPIN(xb_ld(&bar[XB_XGEN(b.x)]) == gen, bar);
;             __builtin_amdgcn_fence(__ATOMIC_ACQUIRE, "agent");
;             asm volatile("s_waitcnt vmcnt(0)" ::: "memory");
;         }
;     }
;     __syncthreads();
; }
.LBB0_823:
	s_cmp_lt_i32 s19, 7
	s_cbranch_scc1 .LBB0_877
	s_waitcnt vmcnt(0)
	s_waitcnt vmcnt(0) lgkmcnt(0)
	s_barrier
	s_mov_b64 s[0:1], exec
	v_readlane_b32 s2, v247, 37
	v_readlane_b32 s3, v247, 38
	s_and_b64 s[2:3], s[0:1], s[2:3]
	s_mov_b64 exec, s[2:3]
	s_cbranch_execz .LBB0_876
	v_readlane_b32 s5, v247, 36
	s_and_b32 s2, s90, 31
	s_lshl_b32 s2, s2, 6
	s_add_u32 s2, s62, s2
	s_addc_u32 s3, s63, 0
	s_add_u32 s6, s2, 0xa000
	s_addc_u32 s7, s3, 0
	s_add_u32 s2, s2, 0x8000
	s_addc_u32 s3, s3, 0
	s_and_b32 s5, s5, 7
	s_lshl_b32 s5, s5, 2
	s_lshl_b32 s5, 8, s5
	v_mov_b32_e32 v1, 0
	global_load_dword v3, v1, s[6:7] sc1
	v_mov_b32_e32 v2, 1
	s_mov_b32 s4, 0
	s_waitcnt vmcnt(0) lgkmcnt(0)
	v_cmp_eq_u32_e32 vcc, s5, v3
	s_cbranch_vccnz .Lgrpbar1_same
	buffer_wbl2 sc1
	s_waitcnt vmcnt(0)
.Lgrpbar1_same:
	global_atomic_add v1, v2, s[2:3]

; __device__ __forceinline__ unsigned xb_ld(unsigned* p)              { return __hip_atomic_load(p, __ATOMIC_RELAXED, __HIP_MEMORY_SCOPE_AGENT); }
; __device__ __forceinline__ unsigned xb_add(unsigned* p, unsigned v) { return __hip_atomic_fetch_add(p, v, __ATOMIC_RELAXED, __HIP_MEMORY_SCOPE_AGENT); }
; #define XB_SPIN(cond, bar) do { unsigned _sp = 0; while (cond) { __builtin_amdgcn_s_sleep(1); \
;     if ((++_sp & 255u) == 0u) { if (xb_ld(&(bar)[XB_TMO])) break; if (_sp > XB_SPIN_CAP) { atomicAdd(&(bar)[XB_TMO], 1u); break; } } } } while (0)
; __device__ __forceinline__ void xcd_barrier(const XcdBarrier& b) {
;     asm volatile("s_waitcnt vmcnt(0)" ::: "memory");
;     __syncthreads();
;     if (threadIdx.x == 0) {
;         unsigned* bar = b.bar;
;         __builtin_amdgcn_s_waitcnt(0);
;         unsigned nloc = b.st[0], nx = b.st[1];
;         if (nloc == 0u) { xcd_barrier_complete(bar, b.x, nloc, nx); b.st[0] = nloc; b.st[1] = nx; }
;         const unsigned old = xb_add(&bar[XB_XSUB(b.x)], 1u);
;         const unsigned gen = old / nloc;
;         if (old + 1u == (gen + 1u) * nloc) {
;             __builtin_amdgcn_fence(__ATOMIC_RELEASE, "agent");
;             asm volatile("s_waitcnt vmcnt(0)" ::: "memory");
;             const unsigned og = xb_add(&bar[XB_TOP], 1u);
;             const unsigned tg = og / nx;
;             if (og + 1u == (tg + 1u) * nx) xb_add(&bar[XB_TOPGEN], 1u);
;             else XB_SPIN(xb_ld(&bar[XB_TOPGEN]) == tg, bar);
;             __builtin_amdgcn_fence(__ATOMIC_ACQUIRE, "agent");
;             xb_add(&bar[XB_XGEN(b.x)], 1u);
;             asm volatile("s_waitcnt vmcnt(0)" ::: "memory");
;         } else {
;             XB_SPIN(xb_ld(&bar[XB_XGEN(b.x)]) == gen, bar);
;             __builtin_amdgcn_fence(__ATOMIC_ACQUIRE, "agent");
;             asm volatile("s_waitcnt vmcnt(0)" ::: "memory");
;         }
;     }
;     __syncthreads();
; }
.LBB0_902:
	s_cmp_lt_i32 s19, 9
	s_cbranch_scc1 .LBB0_956
	s_waitcnt vmcnt(0)
	s_waitcnt vmcnt(0) lgkmcnt(0)
	s_barrier
	s_mov_b64 s[0:1], exec
	v_readlane_b32 s2, v247, 37
	v_readlane_b32 s3, v247, 38
	s_and_b64 s[2:3], s[0:1], s[2:3]
	s_mov_b64 exec, s[2:3]
	s_cbranch_execz .LBB0_955
	v_readlane_b32 s5, v247, 36
	s_and_b32 s2, s90, 31
	s_lshl_b32 s2, s2, 6
	s_add_u32 s2, s62, s2
	s_addc_u32 s3, s63, 0
	s_add_u32 s6, s2, 0xa000
	s_addc_u32 s7, s3, 0
	s_add_u32 s2, s2, 0x9000
	s_addc_u32 s3, s3, 0
	s_and_b32 s5, s5, 7
	s_lshl_b32 s5, s5, 2
	s_lshl_b32 s5, 8, s5
	v_mov_b32_e32 v1, 0
	global_load_dword v3, v1, s[6:7] sc1
	v_mov_b32_e32 v2, 1
	s_mov_b32 s4, 0
	s_waitcnt vmcnt(0) lgkmcnt(0)
	v_cmp_eq_u32_e32 vcc, s5, v3
	s_cbranch_vccnz .Lgrpbar0_same
	buffer_wbl2 sc1
	s_waitcnt vmcnt(0)
